# attention tile loop unrolled by two: LDS double buffer selected by immediate offsets, no per-tile address arithmetic or buffer-select SALU
# speedup vs baseline: 1.0078x; 1.0078x over previous
.Lattn_noprio:
	v_add_u32_e32 v206, v110, v142
	v_add_u32_e32 v207, v138, v143
	s_branch .LBB0_175
.LBB0_175:
	s_barrier
	ds_read_b128 v[162:165], v206
	ds_read_b128 v[166:169], v206 offset:64
	ds_read_b128 v[170:173], v206 offset:128
	ds_read_b128 v[174:177], v206 offset:3584
	ds_read_b128 v[178:181], v206 offset:3648
	ds_read_b128 v[182:185], v206 offset:3712
	ds_read_b128 v[186:189], v206 offset:7168
	ds_read_b128 v[214:217], v206 offset:7232
	ds_read_b128 v[218:221], v206 offset:7296
	ds_read_b128 v[222:225], v206 offset:10752
	ds_read_b128 v[226:229], v206 offset:10816
	ds_read_b128 v[230:233], v206 offset:10880
	global_load_dwordx4 v[72:75], v[136:137], off
	global_load_dwordx4 v[68:71], v[134:135], off
	global_load_dwordx4 v[64:67], v[132:133], off
	s_and_b32 s21, s7, 15
	s_cbranch_scc0 .Lattn_refresh_0
	s_waitcnt lgkmcnt(9)
	v_mfma_f32_16x16x32_bf16 v[92:95], v[162:165], v[0:3], v[148:151]
	v_mfma_f32_16x16x32_bf16 v[76:79], v[162:165], v[8:11], v[152:155]
	ds_read_b64 v[234:235], v207 offset:14336
	ds_read_b64 v[236:237], v207 offset:14368
	v_mfma_f32_16x16x32_bf16 v[92:95], v[166:169], v[4:7], v[92:95]
	v_mfma_f32_16x16x32_bf16 v[76:79], v[166:169], v[12:15], v[76:79]
	ds_read_b64 v[238:239], v207 offset:14400
	ds_read_b64 v[240:241], v207 offset:14432
	v_mfma_f32_16x16x32_bf16 v[92:95], v[170:173], v[16:19], v[92:95]
	v_mfma_f32_16x16x32_bf16 v[76:79], v[170:173], v[20:23], v[76:79]
	ds_read_b64 v[242:243], v207 offset:16640
	ds_read_b64 v[244:245], v207 offset:16672
	s_waitcnt lgkmcnt(12)
	v_mfma_f32_16x16x32_bf16 v[96:99], v[174:177], v[0:3], v[148:151]
	v_mfma_f32_16x16x32_bf16 v[80:83], v[174:177], v[8:11], v[152:155]
	ds_read_b64 v[246:247], v207 offset:16704
	v_mfma_f32_16x16x32_bf16 v[96:99], v[178:181], v[4:7], v[96:99]
	v_mfma_f32_16x16x32_bf16 v[80:83], v[178:181], v[12:15], v[80:83]
	ds_read_b64 v[248:249], v207 offset:16736
	v_mfma_f32_16x16x32_bf16 v[96:99], v[182:185], v[16:19], v[96:99]
	v_mfma_f32_16x16x32_bf16 v[80:83], v[182:185], v[20:23], v[80:83]
	ds_read_b64 v[162:163], v207 offset:18944
	s_waitcnt lgkmcnt(12)
	v_mfma_f32_16x16x32_bf16 v[100:103], v[186:189], v[0:3], v[148:151]
	v_mfma_f32_16x16x32_bf16 v[84:87], v[186:189], v[8:11], v[152:155]
	ds_read_b64 v[164:165], v207 offset:18976
	v_mfma_f32_16x16x32_bf16 v[100:103], v[214:217], v[4:7], v[100:103]
	v_mfma_f32_16x16x32_bf16 v[84:87], v[214:217], v[12:15], v[84:87]
	ds_read_b64 v[166:167], v207 offset:19008
	v_mfma_f32_16x16x32_bf16 v[100:103], v[218:221], v[16:19], v[100:103]
	v_mfma_f32_16x16x32_bf16 v[84:87], v[218:221], v[20:23], v[84:87]
	ds_read_b64 v[168:169], v207 offset:19040
	s_waitcnt lgkmcnt(12)
	v_mfma_f32_16x16x32_bf16 v[104:107], v[222:225], v[0:3], v[148:151]
	v_mfma_f32_16x16x32_bf16 v[88:91], v[222:225], v[8:11], v[152:155]
	ds_read_b64 v[170:171], v207 offset:21248
	v_mfma_f32_16x16x32_bf16 v[104:107], v[226:229], v[4:7], v[104:107]
	v_mfma_f32_16x16x32_bf16 v[88:91], v[226:229], v[12:15], v[88:91]
	ds_read_b64 v[172:173], v207 offset:21280
	v_mfma_f32_16x16x32_bf16 v[104:107], v[230:233], v[16:19], v[104:107]
	v_mfma_f32_16x16x32_bf16 v[88:91], v[230:233], v[20:23], v[88:91]
	s_waitcnt lgkmcnt(13)
	ds_read_b64 v[174:175], v207 offset:21312
	ds_read_b64 v[176:177], v207 offset:21344
.Lattn_sm_0:
	v_exp_f32_e32 v92, v92
	v_exp_f32_e32 v93, v93
	v_exp_f32_e32 v94, v94
	v_exp_f32_e32 v95, v95
	v_exp_f32_e32 v96, v96
	v_exp_f32_e32 v97, v97
	v_exp_f32_e32 v98, v98
	v_exp_f32_e32 v99, v99
	v_exp_f32_e32 v100, v100
	v_exp_f32_e32 v101, v101
	v_exp_f32_e32 v102, v102
	v_exp_f32_e32 v103, v103
	v_exp_f32_e32 v104, v104
	v_exp_f32_e32 v105, v105
	v_exp_f32_e32 v106, v106
	v_exp_f32_e32 v107, v107
	v_cvt_pk_bf16_f32 v92, v92, v93
	v_cvt_pk_bf16_f32 v93, v94, v95
	v_cvt_pk_bf16_f32 v94, v96, v97
	v_cvt_pk_bf16_f32 v95, v98, v99
	v_cvt_pk_bf16_f32 v96, v100, v101
	v_cvt_pk_bf16_f32 v97, v102, v103
	v_cvt_pk_bf16_f32 v98, v104, v105
	v_cvt_pk_bf16_f32 v99, v106, v107
	v_exp_f32_e32 v76, v76
	v_exp_f32_e32 v77, v77
	v_exp_f32_e32 v78, v78
	v_exp_f32_e32 v79, v79
	v_exp_f32_e32 v80, v80
	v_exp_f32_e32 v81, v81
	v_exp_f32_e32 v82, v82
	v_exp_f32_e32 v83, v83
	v_exp_f32_e32 v84, v84
	v_exp_f32_e32 v85, v85
	v_exp_f32_e32 v86, v86
	v_exp_f32_e32 v87, v87
	v_exp_f32_e32 v88, v88
	v_exp_f32_e32 v89, v89
	v_exp_f32_e32 v90, v90
	v_exp_f32_e32 v91, v91
	v_cvt_pk_bf16_f32 v76, v76, v77
	v_cvt_pk_bf16_f32 v77, v78, v79
	v_cvt_pk_bf16_f32 v78, v80, v81
	v_cvt_pk_bf16_f32 v79, v82, v83
	v_cvt_pk_bf16_f32 v80, v84, v85
	v_cvt_pk_bf16_f32 v81, v86, v87
	v_cvt_pk_bf16_f32 v82, v88, v89
	v_cvt_pk_bf16_f32 v83, v90, v91
	s_add_i32 s7, s7, 1
	s_waitcnt vmcnt(2)
	ds_write_b128 v139, v[72:75] offset:23552
	s_waitcnt vmcnt(0)
	ds_write_b128 v116, v[64:67] offset:37888
	s_and_b64 vcc, exec, s[42:43]
	s_cbranch_vccz .Lattn_skipw_0
	ds_write_b128 v140, v[68:71] offset:23552
.Lattn_skipw_0:
	s_waitcnt lgkmcnt(14)
	v_mfma_f32_16x16x32_bf16 v[60:63], v[234:237], v[92:95], v[60:63]
	v_mfma_f32_16x16x32_bf16 v[56:59], v[234:237], v[76:79], v[56:59]
	v_mfma_f32_16x16x32_bf16 v[60:63], v[238:241], v[96:99], v[60:63]
	v_mfma_f32_16x16x32_bf16 v[56:59], v[238:241], v[80:83], v[56:59]
	s_waitcnt lgkmcnt(10)
	v_mfma_f32_16x16x32_bf16 v[52:55], v[242:245], v[92:95], v[52:55]
	v_mfma_f32_16x16x32_bf16 v[48:51], v[242:245], v[76:79], v[48:51]
	v_mfma_f32_16x16x32_bf16 v[52:55], v[246:249], v[96:99], v[52:55]
	v_mfma_f32_16x16x32_bf16 v[48:51], v[246:249], v[80:83], v[48:51]
	s_waitcnt lgkmcnt(6)
	v_mfma_f32_16x16x32_bf16 v[44:47], v[162:165], v[92:95], v[44:47]
	v_mfma_f32_16x16x32_bf16 v[40:43], v[162:165], v[76:79], v[40:43]
	v_mfma_f32_16x16x32_bf16 v[44:47], v[166:169], v[96:99], v[44:47]
	v_mfma_f32_16x16x32_bf16 v[40:43], v[166:169], v[80:83], v[40:43]
	s_waitcnt lgkmcnt(2)
	v_mfma_f32_16x16x32_bf16 v[36:39], v[170:173], v[92:95], v[36:39]
	v_mfma_f32_16x16x32_bf16 v[32:35], v[170:173], v[76:79], v[32:35]
	v_mfma_f32_16x16x32_bf16 v[36:39], v[174:177], v[96:99], v[36:39]
	v_mfma_f32_16x16x32_bf16 v[32:35], v[174:177], v[80:83], v[32:35]
	v_mfma_f32_16x16x32_bf16 v[28:31], v[250:253], v[92:95], v[28:31]
	v_mfma_f32_16x16x32_bf16 v[24:27], v[250:253], v[76:79], v[24:27]
	v_mfma_f32_16x16x32_bf16 v[28:31], v[250:253], v[96:99], v[28:31]
	v_mfma_f32_16x16x32_bf16 v[24:27], v[250:253], v[80:83], v[24:27]
	v_lshl_add_u64 v[132:133], v[132:133], 0, s[50:51]
	v_lshl_add_u64 v[134:135], v[134:135], 0, s[4:5]
	v_lshl_add_u64 v[136:137], v[136:137], 0, s[4:5]
	s_cmp_eq_u32 s6, s7
	s_waitcnt lgkmcnt(0)
	s_cbranch_scc1 .Lattn_exit1
	s_barrier
	ds_read_b128 v[162:165], v206 offset:23552
	ds_read_b128 v[166:169], v206 offset:23616
	ds_read_b128 v[170:173], v206 offset:23680
	ds_read_b128 v[174:177], v206 offset:27136
	ds_read_b128 v[178:181], v206 offset:27200
	ds_read_b128 v[182:185], v206 offset:27264
	ds_read_b128 v[186:189], v206 offset:30720
	ds_read_b128 v[214:217], v206 offset:30784
	ds_read_b128 v[218:221], v206 offset:30848
	ds_read_b128 v[222:225], v206 offset:34304
	ds_read_b128 v[226:229], v206 offset:34368
	ds_read_b128 v[230:233], v206 offset:34432
	global_load_dwordx4 v[72:75], v[136:137], off
	global_load_dwordx4 v[68:71], v[134:135], off
	global_load_dwordx4 v[64:67], v[132:133], off
	s_and_b32 s21, s7, 15
	s_cbranch_scc0 .Lattn_refresh_1
	s_waitcnt lgkmcnt(9)
	v_mfma_f32_16x16x32_bf16 v[92:95], v[162:165], v[0:3], v[148:151]
	v_mfma_f32_16x16x32_bf16 v[76:79], v[162:165], v[8:11], v[152:155]
	ds_read_b64 v[234:235], v207 offset:37888
	ds_read_b64 v[236:237], v207 offset:37920
	v_mfma_f32_16x16x32_bf16 v[92:95], v[166:169], v[4:7], v[92:95]
	v_mfma_f32_16x16x32_bf16 v[76:79], v[166:169], v[12:15], v[76:79]
	ds_read_b64 v[238:239], v207 offset:37952
	ds_read_b64 v[240:241], v207 offset:37984
	v_mfma_f32_16x16x32_bf16 v[92:95], v[170:173], v[16:19], v[92:95]
	v_mfma_f32_16x16x32_bf16 v[76:79], v[170:173], v[20:23], v[76:79]
	ds_read_b64 v[242:243], v207 offset:40192
	ds_read_b64 v[244:245], v207 offset:40224
	s_waitcnt lgkmcnt(12)
	v_mfma_f32_16x16x32_bf16 v[96:99], v[174:177], v[0:3], v[148:151]
	v_mfma_f32_16x16x32_bf16 v[80:83], v[174:177], v[8:11], v[152:155]
	ds_read_b64 v[246:247], v207 offset:40256
	v_mfma_f32_16x16x32_bf16 v[96:99], v[178:181], v[4:7], v[96:99]
	v_mfma_f32_16x16x32_bf16 v[80:83], v[178:181], v[12:15], v[80:83]
	ds_read_b64 v[248:249], v207 offset:40288
	v_mfma_f32_16x16x32_bf16 v[96:99], v[182:185], v[16:19], v[96:99]
	v_mfma_f32_16x16x32_bf16 v[80:83], v[182:185], v[20:23], v[80:83]
	ds_read_b64 v[162:163], v207 offset:42496
	s_waitcnt lgkmcnt(12)
	v_mfma_f32_16x16x32_bf16 v[100:103], v[186:189], v[0:3], v[148:151]
	v_mfma_f32_16x16x32_bf16 v[84:87], v[186:189], v[8:11], v[152:155]
	ds_read_b64 v[164:165], v207 offset:42528
	v_mfma_f32_16x16x32_bf16 v[100:103], v[214:217], v[4:7], v[100:103]
	v_mfma_f32_16x16x32_bf16 v[84:87], v[214:217], v[12:15], v[84:87]
	ds_read_b64 v[166:167], v207 offset:42560
	v_mfma_f32_16x16x32_bf16 v[100:103], v[218:221], v[16:19], v[100:103]
	v_mfma_f32_16x16x32_bf16 v[84:87], v[218:221], v[20:23], v[84:87]
	ds_read_b64 v[168:169], v207 offset:42592
	s_waitcnt lgkmcnt(12)
	v_mfma_f32_16x16x32_bf16 v[104:107], v[222:225], v[0:3], v[148:151]
	v_mfma_f32_16x16x32_bf16 v[88:91], v[222:225], v[8:11], v[152:155]
	ds_read_b64 v[170:171], v207 offset:44800
	v_mfma_f32_16x16x32_bf16 v[104:107], v[226:229], v[4:7], v[104:107]
	v_mfma_f32_16x16x32_bf16 v[88:91], v[226:229], v[12:15], v[88:91]
	ds_read_b64 v[172:173], v207 offset:44832
	v_mfma_f32_16x16x32_bf16 v[104:107], v[230:233], v[16:19], v[104:107]
	v_mfma_f32_16x16x32_bf16 v[88:91], v[230:233], v[20:23], v[88:91]
	s_waitcnt lgkmcnt(13)
	ds_read_b64 v[174:175], v207 offset:44864
	ds_read_b64 v[176:177], v207 offset:44896
.Lattn_sm_1:
	v_exp_f32_e32 v92, v92
	v_exp_f32_e32 v93, v93
	v_exp_f32_e32 v94, v94
	v_exp_f32_e32 v95, v95
	v_exp_f32_e32 v96, v96
	v_exp_f32_e32 v97, v97
	v_exp_f32_e32 v98, v98
	v_exp_f32_e32 v99, v99
	v_exp_f32_e32 v100, v100
	v_exp_f32_e32 v101, v101
	v_exp_f32_e32 v102, v102
	v_exp_f32_e32 v103, v103
	v_exp_f32_e32 v104, v104
	v_exp_f32_e32 v105, v105
	v_exp_f32_e32 v106, v106
	v_exp_f32_e32 v107, v107
	v_cvt_pk_bf16_f32 v92, v92, v93
	v_cvt_pk_bf16_f32 v93, v94, v95
	v_cvt_pk_bf16_f32 v94, v96, v97
	v_cvt_pk_bf16_f32 v95, v98, v99
	v_cvt_pk_bf16_f32 v96, v100, v101
	v_cvt_pk_bf16_f32 v97, v102, v103
	v_cvt_pk_bf16_f32 v98, v104, v105
	v_cvt_pk_bf16_f32 v99, v106, v107
	v_exp_f32_e32 v76, v76
	v_exp_f32_e32 v77, v77
	v_exp_f32_e32 v78, v78
	v_exp_f32_e32 v79, v79
	v_exp_f32_e32 v80, v80
	v_exp_f32_e32 v81, v81
	v_exp_f32_e32 v82, v82
	v_exp_f32_e32 v83, v83
	v_exp_f32_e32 v84, v84
	v_exp_f32_e32 v85, v85
	v_exp_f32_e32 v86, v86
	v_exp_f32_e32 v87, v87
	v_exp_f32_e32 v88, v88
	v_exp_f32_e32 v89, v89
	v_exp_f32_e32 v90, v90
	v_exp_f32_e32 v91, v91
	v_cvt_pk_bf16_f32 v76, v76, v77
	v_cvt_pk_bf16_f32 v77, v78, v79
	v_cvt_pk_bf16_f32 v78, v80, v81
	v_cvt_pk_bf16_f32 v79, v82, v83
	v_cvt_pk_bf16_f32 v80, v84, v85
	v_cvt_pk_bf16_f32 v81, v86, v87
	v_cvt_pk_bf16_f32 v82, v88, v89
	v_cvt_pk_bf16_f32 v83, v90, v91
	s_add_i32 s7, s7, 1
	s_waitcnt vmcnt(2)
	ds_write_b128 v139, v[72:75]
	s_waitcnt vmcnt(0)
	ds_write_b128 v116, v[64:67] offset:14336
	s_and_b64 vcc, exec, s[42:43]
	s_cbranch_vccz .Lattn_skipw_1
	ds_write_b128 v140, v[68:71]
.Lattn_skipw_1:
	s_waitcnt lgkmcnt(14)
	v_mfma_f32_16x16x32_bf16 v[60:63], v[234:237], v[92:95], v[60:63]
	v_mfma_f32_16x16x32_bf16 v[56:59], v[234:237], v[76:79], v[56:59]
	v_mfma_f32_16x16x32_bf16 v[60:63], v[238:241], v[96:99], v[60:63]
	v_mfma_f32_16x16x32_bf16 v[56:59], v[238:241], v[80:83], v[56:59]
	s_waitcnt lgkmcnt(10)
	v_mfma_f32_16x16x32_bf16 v[52:55], v[242:245], v[92:95], v[52:55]
	v_mfma_f32_16x16x32_bf16 v[48:51], v[242:245], v[76:79], v[48:51]
	v_mfma_f32_16x16x32_bf16 v[52:55], v[246:249], v[96:99], v[52:55]
	v_mfma_f32_16x16x32_bf16 v[48:51], v[246:249], v[80:83], v[48:51]
	s_waitcnt lgkmcnt(6)
	v_mfma_f32_16x16x32_bf16 v[44:47], v[162:165], v[92:95], v[44:47]
	v_mfma_f32_16x16x32_bf16 v[40:43], v[162:165], v[76:79], v[40:43]
	v_mfma_f32_16x16x32_bf16 v[44:47], v[166:169], v[96:99], v[44:47]
	v_mfma_f32_16x16x32_bf16 v[40:43], v[166:169], v[80:83], v[40:43]
	s_waitcnt lgkmcnt(2)
	v_mfma_f32_16x16x32_bf16 v[36:39], v[170:173], v[92:95], v[36:39]
	v_mfma_f32_16x16x32_bf16 v[32:35], v[170:173], v[76:79], v[32:35]
	v_mfma_f32_16x16x32_bf16 v[36:39], v[174:177], v[96:99], v[36:39]
	v_mfma_f32_16x16x32_bf16 v[32:35], v[174:177], v[80:83], v[32:35]
	v_mfma_f32_16x16x32_bf16 v[28:31], v[250:253], v[92:95], v[28:31]
	v_mfma_f32_16x16x32_bf16 v[24:27], v[250:253], v[76:79], v[24:27]
	v_mfma_f32_16x16x32_bf16 v[28:31], v[250:253], v[96:99], v[28:31]
	v_mfma_f32_16x16x32_bf16 v[24:27], v[250:253], v[80:83], v[24:27]
	v_lshl_add_u64 v[132:133], v[132:133], 0, s[50:51]
	v_lshl_add_u64 v[134:135], v[134:135], 0, s[4:5]
	v_lshl_add_u64 v[136:137], v[136:137], 0, s[4:5]
	s_cmp_eq_u32 s6, s7
	s_waitcnt lgkmcnt(0)
	s_cbranch_scc0 .LBB0_175
	s_barrier
	s_mov_b32 s10, 0
	s_branch .LBB0_161
.Lattn_exit1:
	s_barrier
	s_movk_i32 s10, 0x5c00
	s_branch .LBB0_161
.Lattn_refresh_0:
	s_waitcnt lgkmcnt(9)
	v_mfma_f32_16x16x32_bf16 v[92:95], v[162:165], v[0:3], 0
	v_mfma_f32_16x16x32_bf16 v[76:79], v[162:165], v[8:11], 0
	ds_read_b64 v[234:235], v207 offset:14336
	ds_read_b64 v[236:237], v207 offset:14368
	v_mfma_f32_16x16x32_bf16 v[92:95], v[166:169], v[4:7], v[92:95]
	v_mfma_f32_16x16x32_bf16 v[76:79], v[166:169], v[12:15], v[76:79]
	ds_read_b64 v[238:239], v207 offset:14400
	ds_read_b64 v[240:241], v207 offset:14432
	v_mfma_f32_16x16x32_bf16 v[92:95], v[170:173], v[16:19], v[92:95]
	v_mfma_f32_16x16x32_bf16 v[76:79], v[170:173], v[20:23], v[76:79]
	ds_read_b64 v[242:243], v207 offset:16640
	ds_read_b64 v[244:245], v207 offset:16672
	s_waitcnt lgkmcnt(12)
	v_mfma_f32_16x16x32_bf16 v[96:99], v[174:177], v[0:3], 0
	v_mfma_f32_16x16x32_bf16 v[80:83], v[174:177], v[8:11], 0
	ds_read_b64 v[246:247], v207 offset:16704
	v_mfma_f32_16x16x32_bf16 v[96:99], v[178:181], v[4:7], v[96:99]
	v_mfma_f32_16x16x32_bf16 v[80:83], v[178:181], v[12:15], v[80:83]
	ds_read_b64 v[248:249], v207 offset:16736
	v_mfma_f32_16x16x32_bf16 v[96:99], v[182:185], v[16:19], v[96:99]
	v_mfma_f32_16x16x32_bf16 v[80:83], v[182:185], v[20:23], v[80:83]
	ds_read_b64 v[162:163], v207 offset:18944
	s_waitcnt lgkmcnt(12)
	v_mfma_f32_16x16x32_bf16 v[100:103], v[186:189], v[0:3], 0
	v_mfma_f32_16x16x32_bf16 v[84:87], v[186:189], v[8:11], 0
	ds_read_b64 v[164:165], v207 offset:18976
	v_mfma_f32_16x16x32_bf16 v[100:103], v[214:217], v[4:7], v[100:103]
	v_mfma_f32_16x16x32_bf16 v[84:87], v[214:217], v[12:15], v[84:87]
	ds_read_b64 v[166:167], v207 offset:19008
	v_mfma_f32_16x16x32_bf16 v[100:103], v[218:221], v[16:19], v[100:103]
	v_mfma_f32_16x16x32_bf16 v[84:87], v[218:221], v[20:23], v[84:87]
	ds_read_b64 v[168:169], v207 offset:19040
	s_waitcnt lgkmcnt(12)
	v_mfma_f32_16x16x32_bf16 v[104:107], v[222:225], v[0:3], 0
	v_mfma_f32_16x16x32_bf16 v[88:91], v[222:225], v[8:11], 0
	ds_read_b64 v[170:171], v207 offset:21248
	v_mfma_f32_16x16x32_bf16 v[104:107], v[226:229], v[4:7], v[104:107]
	v_mfma_f32_16x16x32_bf16 v[88:91], v[226:229], v[12:15], v[88:91]
	ds_read_b64 v[172:173], v207 offset:21280
	v_mfma_f32_16x16x32_bf16 v[104:107], v[230:233], v[16:19], v[104:107]
	v_mfma_f32_16x16x32_bf16 v[88:91], v[230:233], v[20:23], v[88:91]
	s_waitcnt lgkmcnt(13)
	ds_read_b64 v[174:175], v207 offset:21312
	ds_read_b64 v[176:177], v207 offset:21344
	s_nop 7
	v_max_f32_e32 v127, v93, v93
	v_max_f32_e32 v129, v92, v92
	v_max_f32_e32 v127, v129, v127
	v_max_f32_e32 v129, v95, v95
	v_max_f32_e32 v131, v94, v94
	v_max_f32_e32 v129, v131, v129
	v_max_f32_e32 v131, v99, v99
	v_max_f32_e32 v147, v98, v98
	v_max_f32_e32 v131, v147, v131
	v_max3_f32 v131, v96, v97, v131
	v_max3_f32 v127, v127, v129, v131
	v_max_f32_e32 v129, v103, v103
	v_max_f32_e32 v131, v102, v102
	v_max_f32_e32 v129, v131, v129
	v_max_f32_e32 v131, v107, v107
	v_max_f32_e32 v147, v106, v106
	v_max_f32_e32 v131, v147, v131
	v_max3_f32 v129, v100, v101, v129
	v_max3_f32 v131, v104, v105, v131
	v_max3_f32 v127, v127, v129, v131
	ds_bpermute_b32 v129, v145, v127
	s_waitcnt lgkmcnt(0)
	v_max_f32_e32 v129, v129, v129
	v_max_f32_e32 v127, v127, v129
	ds_bpermute_b32 v129, v144, v127
	s_waitcnt lgkmcnt(0)
	v_max3_f32 v127, v130, v127, v129
	v_sub_f32_e32 v129, v130, v127
	v_exp_f32_e32 v130, v129
	s_nop 0
	v_pk_mul_f32 v[62:63], v[62:63], v[130:131] op_sel_hi:[1,0]
	v_pk_mul_f32 v[60:61], v[60:61], v[130:131] op_sel_hi:[1,0]
	v_pk_mul_f32 v[54:55], v[54:55], v[130:131] op_sel_hi:[1,0]
	v_pk_mul_f32 v[52:53], v[52:53], v[130:131] op_sel_hi:[1,0]
	v_pk_mul_f32 v[46:47], v[46:47], v[130:131] op_sel_hi:[1,0]
	v_pk_mul_f32 v[44:45], v[44:45], v[130:131] op_sel_hi:[1,0]
	v_pk_mul_f32 v[38:39], v[38:39], v[130:131] op_sel_hi:[1,0]
	v_pk_mul_f32 v[36:37], v[36:37], v[130:131] op_sel_hi:[1,0]
	v_pk_mul_f32 v[30:31], v[30:31], v[130:131] op_sel_hi:[1,0]
	v_pk_mul_f32 v[28:29], v[28:29], v[130:131] op_sel_hi:[1,0]
	v_mov_b32_e32 v130, v127
	v_xor_b32_e32 v148, 0x80000000, v127
	v_xor_b32_e32 v149, 0x80000000, v127
	v_xor_b32_e32 v150, 0x80000000, v127
	v_xor_b32_e32 v151, 0x80000000, v127
	v_max_f32_e32 v127, v77, v77
	v_max_f32_e32 v129, v76, v76
	v_max_f32_e32 v127, v129, v127
	v_max_f32_e32 v129, v79, v79
	v_max_f32_e32 v131, v78, v78
	v_max_f32_e32 v129, v131, v129
	v_max_f32_e32 v131, v83, v83
	v_max_f32_e32 v147, v82, v82
	v_max_f32_e32 v131, v147, v131
	v_max3_f32 v131, v80, v81, v131
	v_max3_f32 v127, v127, v129, v131
	v_max_f32_e32 v129, v87, v87
	v_max_f32_e32 v131, v86, v86
	v_max_f32_e32 v129, v131, v129
	v_max_f32_e32 v131, v91, v91
	v_max_f32_e32 v147, v90, v90
	v_max_f32_e32 v131, v147, v131
	v_max3_f32 v129, v84, v85, v129
	v_max3_f32 v131, v88, v89, v131
	v_max3_f32 v127, v127, v129, v131
	ds_bpermute_b32 v129, v145, v127
	s_waitcnt lgkmcnt(0)
	v_max_f32_e32 v129, v129, v129
	v_max_f32_e32 v127, v127, v129
	ds_bpermute_b32 v129, v144, v127
	s_waitcnt lgkmcnt(0)
	v_max3_f32 v131, v128, v127, v129
	v_sub_f32_e32 v127, v128, v131
	v_exp_f32_e32 v128, v127
	s_nop 0
	v_pk_mul_f32 v[58:59], v[58:59], v[128:129] op_sel_hi:[1,0]
	v_pk_mul_f32 v[56:57], v[56:57], v[128:129] op_sel_hi:[1,0]
	v_pk_mul_f32 v[50:51], v[50:51], v[128:129] op_sel_hi:[1,0]
	v_pk_mul_f32 v[48:49], v[48:49], v[128:129] op_sel_hi:[1,0]
	v_pk_mul_f32 v[42:43], v[42:43], v[128:129] op_sel_hi:[1,0]
	v_pk_mul_f32 v[40:41], v[40:41], v[128:129] op_sel_hi:[1,0]
	v_pk_mul_f32 v[34:35], v[34:35], v[128:129] op_sel_hi:[1,0]
	v_pk_mul_f32 v[32:33], v[32:33], v[128:129] op_sel_hi:[1,0]
	v_pk_mul_f32 v[26:27], v[26:27], v[128:129] op_sel_hi:[1,0]
	v_pk_mul_f32 v[24:25], v[24:25], v[128:129] op_sel_hi:[1,0]
	v_mov_b32_e32 v128, v131
	v_xor_b32_e32 v152, 0x80000000, v131
	v_xor_b32_e32 v153, 0x80000000, v131
	v_xor_b32_e32 v154, 0x80000000, v131
	v_xor_b32_e32 v155, 0x80000000, v131
	v_pk_add_f32 v[92:93], v[92:93], v[130:131] op_sel_hi:[1,0] neg_lo:[0,1] neg_hi:[0,1]
	v_pk_add_f32 v[94:95], v[94:95], v[130:131] op_sel_hi:[1,0] neg_lo:[0,1] neg_hi:[0,1]
	v_pk_add_f32 v[96:97], v[96:97], v[130:131] op_sel_hi:[1,0] neg_lo:[0,1] neg_hi:[0,1]
	v_pk_add_f32 v[98:99], v[98:99], v[130:131] op_sel_hi:[1,0] neg_lo:[0,1] neg_hi:[0,1]
	v_pk_add_f32 v[100:101], v[100:101], v[130:131] op_sel_hi:[1,0] neg_lo:[0,1] neg_hi:[0,1]
	v_pk_add_f32 v[102:103], v[102:103], v[130:131] op_sel_hi:[1,0] neg_lo:[0,1] neg_hi:[0,1]
	v_pk_add_f32 v[104:105], v[104:105], v[130:131] op_sel_hi:[1,0] neg_lo:[0,1] neg_hi:[0,1]
	v_pk_add_f32 v[106:107], v[106:107], v[130:131] op_sel_hi:[1,0] neg_lo:[0,1] neg_hi:[0,1]
	v_pk_add_f32 v[76:77], v[76:77], v[128:129] op_sel_hi:[1,0] neg_lo:[0,1] neg_hi:[0,1]
	v_pk_add_f32 v[78:79], v[78:79], v[128:129] op_sel_hi:[1,0] neg_lo:[0,1] neg_hi:[0,1]
	v_pk_add_f32 v[80:81], v[80:81], v[128:129] op_sel_hi:[1,0] neg_lo:[0,1] neg_hi:[0,1]
	v_pk_add_f32 v[82:83], v[82:83], v[128:129] op_sel_hi:[1,0] neg_lo:[0,1] neg_hi:[0,1]
	v_pk_add_f32 v[84:85], v[84:85], v[128:129] op_sel_hi:[1,0] neg_lo:[0,1] neg_hi:[0,1]
	v_pk_add_f32 v[86:87], v[86:87], v[128:129] op_sel_hi:[1,0] neg_lo:[0,1] neg_hi:[0,1]
	v_pk_add_f32 v[88:89], v[88:89], v[128:129] op_sel_hi:[1,0] neg_lo:[0,1] neg_hi:[0,1]
	v_pk_add_f32 v[90:91], v[90:91], v[128:129] op_sel_hi:[1,0] neg_lo:[0,1] neg_hi:[0,1]
	s_branch .Lattn_sm_0
.Lattn_refresh_1:
	s_waitcnt lgkmcnt(9)
	v_mfma_f32_16x16x32_bf16 v[92:95], v[162:165], v[0:3], 0
	v_mfma_f32_16x16x32_bf16 v[76:79], v[162:165], v[8:11], 0
	ds_read_b64 v[234:235], v207 offset:37888
	ds_read_b64 v[236:237], v207 offset:37920
	v_mfma_f32_16x16x32_bf16 v[92:95], v[166:169], v[4:7], v[92:95]
	v_mfma_f32_16x16x32_bf16 v[76:79], v[166:169], v[12:15], v[76:79]
	ds_read_b64 v[238:239], v207 offset:37952
	ds_read_b64 v[240:241], v207 offset:37984
	v_mfma_f32_16x16x32_bf16 v[92:95], v[170:173], v[16:19], v[92:95]
	v_mfma_f32_16x16x32_bf16 v[76:79], v[170:173], v[20:23], v[76:79]
	ds_read_b64 v[242:243], v207 offset:40192
	ds_read_b64 v[244:245], v207 offset:40224
	s_waitcnt lgkmcnt(12)
	v_mfma_f32_16x16x32_bf16 v[96:99], v[174:177], v[0:3], 0
	v_mfma_f32_16x16x32_bf16 v[80:83], v[174:177], v[8:11], 0
	ds_read_b64 v[246:247], v207 offset:40256
	v_mfma_f32_16x16x32_bf16 v[96:99], v[178:181], v[4:7], v[96:99]
	v_mfma_f32_16x16x32_bf16 v[80:83], v[178:181], v[12:15], v[80:83]
	ds_read_b64 v[248:249], v207 offset:40288
	v_mfma_f32_16x16x32_bf16 v[96:99], v[182:185], v[16:19], v[96:99]
	v_mfma_f32_16x16x32_bf16 v[80:83], v[182:185], v[20:23], v[80:83]
	ds_read_b64 v[162:163], v207 offset:42496
	s_waitcnt lgkmcnt(12)
	v_mfma_f32_16x16x32_bf16 v[100:103], v[186:189], v[0:3], 0
	v_mfma_f32_16x16x32_bf16 v[84:87], v[186:189], v[8:11], 0
	ds_read_b64 v[164:165], v207 offset:42528
	v_mfma_f32_16x16x32_bf16 v[100:103], v[214:217], v[4:7], v[100:103]
	v_mfma_f32_16x16x32_bf16 v[84:87], v[214:217], v[12:15], v[84:87]
	ds_read_b64 v[166:167], v207 offset:42560
	v_mfma_f32_16x16x32_bf16 v[100:103], v[218:221], v[16:19], v[100:103]
	v_mfma_f32_16x16x32_bf16 v[84:87], v[218:221], v[20:23], v[84:87]
	ds_read_b64 v[168:169], v207 offset:42592
	s_waitcnt lgkmcnt(12)
	v_mfma_f32_16x16x32_bf16 v[104:107], v[222:225], v[0:3], 0
	v_mfma_f32_16x16x32_bf16 v[88:91], v[222:225], v[8:11], 0
	ds_read_b64 v[170:171], v207 offset:44800
	v_mfma_f32_16x16x32_bf16 v[104:107], v[226:229], v[4:7], v[104:107]
	v_mfma_f32_16x16x32_bf16 v[88:91], v[226:229], v[12:15], v[88:91]
	ds_read_b64 v[172:173], v207 offset:44832
	v_mfma_f32_16x16x32_bf16 v[104:107], v[230:233], v[16:19], v[104:107]
	v_mfma_f32_16x16x32_bf16 v[88:91], v[230:233], v[20:23], v[88:91]
	s_waitcnt lgkmcnt(13)
	ds_read_b64 v[174:175], v207 offset:44864
	ds_read_b64 v[176:177], v207 offset:44896
	s_nop 7
	v_max_f32_e32 v127, v93, v93
	v_max_f32_e32 v129, v92, v92
	v_max_f32_e32 v127, v129, v127
	v_max_f32_e32 v129, v95, v95
	v_max_f32_e32 v131, v94, v94
	v_max_f32_e32 v129, v131, v129
	v_max_f32_e32 v131, v99, v99
	v_max_f32_e32 v147, v98, v98
	v_max_f32_e32 v131, v147, v131
	v_max3_f32 v131, v96, v97, v131
	v_max3_f32 v127, v127, v129, v131
	v_max_f32_e32 v129, v103, v103
	v_max_f32_e32 v131, v102, v102
	v_max_f32_e32 v129, v131, v129
	v_max_f32_e32 v131, v107, v107
	v_max_f32_e32 v147, v106, v106
	v_max_f32_e32 v131, v147, v131
	v_max3_f32 v129, v100, v101, v129
	v_max3_f32 v131, v104, v105, v131
	v_max3_f32 v127, v127, v129, v131
	ds_bpermute_b32 v129, v145, v127
	s_waitcnt lgkmcnt(0)
	v_max_f32_e32 v129, v129, v129
	v_max_f32_e32 v127, v127, v129
	ds_bpermute_b32 v129, v144, v127
	s_waitcnt lgkmcnt(0)
	v_max3_f32 v127, v130, v127, v129
	v_sub_f32_e32 v129, v130, v127
	v_exp_f32_e32 v130, v129
	s_nop 0
	v_pk_mul_f32 v[62:63], v[62:63], v[130:131] op_sel_hi:[1,0]
	v_pk_mul_f32 v[60:61], v[60:61], v[130:131] op_sel_hi:[1,0]
	v_pk_mul_f32 v[54:55], v[54:55], v[130:131] op_sel_hi:[1,0]
	v_pk_mul_f32 v[52:53], v[52:53], v[130:131] op_sel_hi:[1,0]
	v_pk_mul_f32 v[46:47], v[46:47], v[130:131] op_sel_hi:[1,0]
	v_pk_mul_f32 v[44:45], v[44:45], v[130:131] op_sel_hi:[1,0]
	v_pk_mul_f32 v[38:39], v[38:39], v[130:131] op_sel_hi:[1,0]
	v_pk_mul_f32 v[36:37], v[36:37], v[130:131] op_sel_hi:[1,0]
	v_pk_mul_f32 v[30:31], v[30:31], v[130:131] op_sel_hi:[1,0]
	v_pk_mul_f32 v[28:29], v[28:29], v[130:131] op_sel_hi:[1,0]
	v_mov_b32_e32 v130, v127
	v_xor_b32_e32 v148, 0x80000000, v127
	v_xor_b32_e32 v149, 0x80000000, v127
	v_xor_b32_e32 v150, 0x80000000, v127
	v_xor_b32_e32 v151, 0x80000000, v127
	v_max_f32_e32 v127, v77, v77
	v_max_f32_e32 v129, v76, v76
	v_max_f32_e32 v127, v129, v127
	v_max_f32_e32 v129, v79, v79
	v_max_f32_e32 v131, v78, v78
	v_max_f32_e32 v129, v131, v129
	v_max_f32_e32 v131, v83, v83
	v_max_f32_e32 v147, v82, v82
	v_max_f32_e32 v131, v147, v131
	v_max3_f32 v131, v80, v81, v131
	v_max3_f32 v127, v127, v129, v131
	v_max_f32_e32 v129, v87, v87
	v_max_f32_e32 v131, v86, v86
	v_max_f32_e32 v129, v131, v129
	v_max_f32_e32 v131, v91, v91
	v_max_f32_e32 v147, v90, v90
	v_max_f32_e32 v131, v147, v131
	v_max3_f32 v129, v84, v85, v129
	v_max3_f32 v131, v88, v89, v131
	v_max3_f32 v127, v127, v129, v131
	ds_bpermute_b32 v129, v145, v127
	s_waitcnt lgkmcnt(0)
	v_max_f32_e32 v129, v129, v129
	v_max_f32_e32 v127, v127, v129
	ds_bpermute_b32 v129, v144, v127
	s_waitcnt lgkmcnt(0)
	v_max3_f32 v131, v128, v127, v129
	v_sub_f32_e32 v127, v128, v131
	v_exp_f32_e32 v128, v127
	s_nop 0
	v_pk_mul_f32 v[58:59], v[58:59], v[128:129] op_sel_hi:[1,0]
	v_pk_mul_f32 v[56:57], v[56:57], v[128:129] op_sel_hi:[1,0]
	v_pk_mul_f32 v[50:51], v[50:51], v[128:129] op_sel_hi:[1,0]
	v_pk_mul_f32 v[48:49], v[48:49], v[128:129] op_sel_hi:[1,0]
	v_pk_mul_f32 v[42:43], v[42:43], v[128:129] op_sel_hi:[1,0]
	v_pk_mul_f32 v[40:41], v[40:41], v[128:129] op_sel_hi:[1,0]
	v_pk_mul_f32 v[34:35], v[34:35], v[128:129] op_sel_hi:[1,0]
	v_pk_mul_f32 v[32:33], v[32:33], v[128:129] op_sel_hi:[1,0]
	v_pk_mul_f32 v[26:27], v[26:27], v[128:129] op_sel_hi:[1,0]
	v_pk_mul_f32 v[24:25], v[24:25], v[128:129] op_sel_hi:[1,0]
	v_mov_b32_e32 v128, v131
	v_xor_b32_e32 v152, 0x80000000, v131
	v_xor_b32_e32 v153, 0x80000000, v131
	v_xor_b32_e32 v154, 0x80000000, v131
	v_xor_b32_e32 v155, 0x80000000, v131
	v_pk_add_f32 v[92:93], v[92:93], v[130:131] op_sel_hi:[1,0] neg_lo:[0,1] neg_hi:[0,1]
	v_pk_add_f32 v[94:95], v[94:95], v[130:131] op_sel_hi:[1,0] neg_lo:[0,1] neg_hi:[0,1]
	v_pk_add_f32 v[96:97], v[96:97], v[130:131] op_sel_hi:[1,0] neg_lo:[0,1] neg_hi:[0,1]
	v_pk_add_f32 v[98:99], v[98:99], v[130:131] op_sel_hi:[1,0] neg_lo:[0,1] neg_hi:[0,1]
	v_pk_add_f32 v[100:101], v[100:101], v[130:131] op_sel_hi:[1,0] neg_lo:[0,1] neg_hi:[0,1]
	v_pk_add_f32 v[102:103], v[102:103], v[130:131] op_sel_hi:[1,0] neg_lo:[0,1] neg_hi:[0,1]
	v_pk_add_f32 v[104:105], v[104:105], v[130:131] op_sel_hi:[1,0] neg_lo:[0,1] neg_hi:[0,1]
	v_pk_add_f32 v[106:107], v[106:107], v[130:131] op_sel_hi:[1,0] neg_lo:[0,1] neg_hi:[0,1]
	v_pk_add_f32 v[76:77], v[76:77], v[128:129] op_sel_hi:[1,0] neg_lo:[0,1] neg_hi:[0,1]
	v_pk_add_f32 v[78:79], v[78:79], v[128:129] op_sel_hi:[1,0] neg_lo:[0,1] neg_hi:[0,1]
	v_pk_add_f32 v[80:81], v[80:81], v[128:129] op_sel_hi:[1,0] neg_lo:[0,1] neg_hi:[0,1]
	v_pk_add_f32 v[82:83], v[82:83], v[128:129] op_sel_hi:[1,0] neg_lo:[0,1] neg_hi:[0,1]
	v_pk_add_f32 v[84:85], v[84:85], v[128:129] op_sel_hi:[1,0] neg_lo:[0,1] neg_hi:[0,1]
	v_pk_add_f32 v[86:87], v[86:87], v[128:129] op_sel_hi:[1,0] neg_lo:[0,1] neg_hi:[0,1]
	v_pk_add_f32 v[88:89], v[88:89], v[128:129] op_sel_hi:[1,0] neg_lo:[0,1] neg_hi:[0,1]
	v_pk_add_f32 v[90:91], v[90:91], v[128:129] op_sel_hi:[1,0] neg_lo:[0,1] neg_hi:[0,1]
	s_branch .Lattn_sm_1
